# int8 weight conversion as half-workgroup streams: quads of workgroups split K in quarters (128-byte rows), 4-wave LDS counter sync, quad exchange of column maxima through tagged granules
# baseline (speedup 1.0000x reference)
.Lp0_after_colmax:
	v_readlane_b32 s0, v254, 15
	s_lshl_b32 s21, s0, 9
	s_mov_b32 s14, s90
	s_cmpk_gt_i32 s90, 0x69ff
	s_waitcnt lgkmcnt(0)
	s_barrier
	s_cbranch_scc1 .LBB0_115
	v_mbcnt_lo_u32_b32 v135, -1, 0
	v_mbcnt_hi_u32_b32 v135, -1, v135
	v_lshrrev_b32_e32 v136, 3, v135
	v_and_b32_e32 v137, 7, v135
	v_lshlrev_b32_e32 v230, 4, v137
	v_lshlrev_b32_e32 v195, 5, v137
	v_lshlrev_b32_e32 v231, 15, v137
	v_lshl_add_u32 v231, v136, 3, v231
	v_readlane_b32 s62, v254, 17
	v_readlane_b32 s1, v254, 16
	v_readlane_b32 s72, v254, 15
	s_mov_b32 s74, 0x42fe0000
	s_mov_b32 s11, 0
	s_and_b32 s12, s72, 3
	s_lshr_b32 s72, s72, 2
	s_and_b32 s15, s1, 3
	s_lshr_b32 s3, s1, 2
	s_lshl_b32 s72, s72, 1
	s_add_u32 s72, s72, s3
	s_lshl_b32 s17, s3, 11
	s_add_u32 s17, s17, 0x21000
	s_lshl_b32 s3, s3, 4
	s_add_u32 s3, s3, 0x22000
	v_mov_b32_e32 v250, s3
	v_mov_b32_e32 v251, 0
	ds_write_b32 v250, v251
	v_mov_b32_e32 v251, 1
	v_and_b32_e32 v252, 31, v135
	v_lshlrev_b32_e32 v252, 5, v252
	s_mov_b32 s16, 0
	s_mov_b32 s53, 0
	s_lshl_b32 s52, s12, 10
	s_lshl_b32 s3, s15, 8
	s_add_u32 s52, s52, s3
	s_lshl_b32 s3, s72, 11
	s_add_u32 s3, s3, 0x8000
	s_cmp_ge_u32 s72, 112
	s_cselect_b32 s10, 0x48000, 0
	s_add_u32 s3, s3, s10
	s_add_u32 s50, s34, s3
	s_addc_u32 s51, s35, 0
	s_waitcnt lgkmcnt(0)
	s_barrier
	v_lshlrev_b32_e32 v139, 10, v137
	v_lshl_add_u32 v139, v136, 2, v139
	v_add_u32_e32 v139, s62, v139
	v_lshlrev_b32_e32 v174, 2, v135
	v_xor_b32_e32 v192, 0x20, v174
	v_xor_b32_e32 v193, 0x40, v174
	v_xor_b32_e32 v194, 0x80, v174
	v_lshrrev_b32_e32 v175, 4, v135
	v_and_b32_e32 v176, 15, v135
	v_lshlrev_b32_e32 v212, 8, v175
	v_lshl_add_u32 v212, v176, 4, v212
	v_add_u32_e32 v212, s62, v212
	v_lshlrev_b32_e32 v213, 12, v175
	v_lshl_add_u32 v213, v176, 4, v213
	v_readlane_b32 s48, v255, 47
	v_readlane_b32 s49, v255, 48
	v_mul_u32_u24_e32 v138, 0x20000, v136
	v_lshl_add_u32 v138, v137, 4, v138
	s_mul_i32 s3, s52, 0x8000
	s_nop 1
	s_add_u32 s48, s48, s3
	s_addc_u32 s49, s49, 0
	s_mov_b32 s0, s72
	s_cmp_ge_u32 s0, 0x100
	s_cbranch_scc1 .Lc32_gates_done
	s_lshl_b32 s3, s0, 7
	s_add_u32 s56, s48, s3
	s_addc_u32 s57, s49, 0
	global_load_dwordx4 v[6:9], v138, s[56:57]
	s_add_u32 s56, s56, 0x8000
	s_addc_u32 s57, s57, 0
	global_load_dwordx4 v[10:13], v138, s[56:57]
	s_add_u32 s56, s56, 0x8000
	s_addc_u32 s57, s57, 0
	global_load_dwordx4 v[14:17], v138, s[56:57]
	s_add_u32 s56, s56, 0x8000
	s_addc_u32 s57, s57, 0
	global_load_dwordx4 v[18:21], v138, s[56:57]
	s_add_u32 s56, s56, 0xe8000
	s_addc_u32 s57, s57, 0
	global_load_dwordx4 v[22:25], v138, s[56:57]
	s_add_u32 s56, s56, 0x8000
	s_addc_u32 s57, s57, 0
	global_load_dwordx4 v[26:29], v138, s[56:57]
	s_add_u32 s56, s56, 0x8000
	s_addc_u32 s57, s57, 0
	global_load_dwordx4 v[30:33], v138, s[56:57]
	s_add_u32 s56, s56, 0x8000
	s_addc_u32 s57, s57, 0
	global_load_dwordx4 v[34:37], v138, s[56:57]
	s_add_u32 s56, s56, 0xe8000
	s_addc_u32 s57, s57, 0
	global_load_dwordx4 v[38:41], v138, s[56:57]
	s_add_u32 s56, s56, 0x8000
	s_addc_u32 s57, s57, 0
	global_load_dwordx4 v[42:45], v138, s[56:57]
	s_add_u32 s56, s56, 0x8000
	s_addc_u32 s57, s57, 0
	global_load_dwordx4 v[46:49], v138, s[56:57]
	s_add_u32 s56, s56, 0x8000
	s_addc_u32 s57, s57, 0
	global_load_dwordx4 v[50:53], v138, s[56:57]
	s_add_u32 s56, s56, 0xe8000
	s_addc_u32 s57, s57, 0
	global_load_dwordx4 v[54:57], v138, s[56:57]
	s_add_u32 s56, s56, 0x8000
	s_addc_u32 s57, s57, 0
	global_load_dwordx4 v[58:61], v138, s[56:57]
	s_add_u32 s56, s56, 0x8000
	s_addc_u32 s57, s57, 0
	global_load_dwordx4 v[62:65], v138, s[56:57]
	s_add_u32 s56, s56, 0x8000
	s_addc_u32 s57, s57, 0
	global_load_dwordx4 v[66:69], v138, s[56:57]
	s_add_u32 s56, s56, 0xe8000
	s_addc_u32 s57, s57, 0
	global_load_dwordx4 v[70:73], v138, s[56:57]
	s_add_u32 s56, s56, 0x8000
	s_addc_u32 s57, s57, 0
	global_load_dwordx4 v[74:77], v138, s[56:57]
	s_add_u32 s56, s56, 0x8000
	s_addc_u32 s57, s57, 0
	global_load_dwordx4 v[78:81], v138, s[56:57]
	s_add_u32 s56, s56, 0x8000
	s_addc_u32 s57, s57, 0
	global_load_dwordx4 v[82:85], v138, s[56:57]
	s_add_u32 s56, s56, 0xe8000
	s_addc_u32 s57, s57, 0
	global_load_dwordx4 v[86:89], v138, s[56:57]
	s_add_u32 s56, s56, 0x8000
	s_addc_u32 s57, s57, 0
	global_load_dwordx4 v[90:93], v138, s[56:57]
	s_add_u32 s56, s56, 0x8000
	s_addc_u32 s57, s57, 0
	global_load_dwordx4 v[94:97], v138, s[56:57]
	s_add_u32 s56, s56, 0x8000
	s_addc_u32 s57, s57, 0
	global_load_dwordx4 v[98:101], v138, s[56:57]
	s_add_u32 s56, s56, 0xe8000
	s_addc_u32 s57, s57, 0
	global_load_dwordx4 v[102:105], v138, s[56:57]
	s_add_u32 s56, s56, 0x8000
	s_addc_u32 s57, s57, 0
	global_load_dwordx4 v[106:109], v138, s[56:57]
	s_add_u32 s56, s56, 0x8000
	s_addc_u32 s57, s57, 0
	global_load_dwordx4 v[110:113], v138, s[56:57]
	s_add_u32 s56, s56, 0x8000
	s_addc_u32 s57, s57, 0
	global_load_dwordx4 v[114:117], v138, s[56:57]
	s_add_u32 s56, s56, 0xe8000
	s_addc_u32 s57, s57, 0
	global_load_dwordx4 v[118:121], v138, s[56:57]
	s_add_u32 s56, s56, 0x8000
	s_addc_u32 s57, s57, 0
	global_load_dwordx4 v[122:125], v138, s[56:57]
	s_add_u32 s56, s56, 0x8000
	s_addc_u32 s57, s57, 0
	global_load_dwordx4 v[126:129], v138, s[56:57]
	s_add_u32 s56, s56, 0x8000
	s_addc_u32 s57, s57, 0
	global_load_dwordx4 v[130:133], v138, s[56:57]
.Lc32_gates_loop:
	s_lshl_b32 s2, s0, 5
	s_add_u32 s53, s53, 1
	s_mov_b32 s60, s2
	s_lshl_b32 s63, s11, 10
	s_add_u32 s63, s63, s17
	s_lshl_b32 s3, s15, 7
	s_add_u32 s3, s3, s63
	v_add_u32_e32 v172, s3, v230
	v_add_u32_e32 v173, s63, v230
	s_waitcnt vmcnt(0)
	v_max3_f32 v216, |v6|, |v10|, |v14|
	v_max3_f32 v216, v216, |v18|, |v22|
	v_max3_f32 v216, v216, |v26|, |v30|
	v_max3_f32 v216, v216, |v34|, |v38|
	v_max3_f32 v216, v216, |v42|, |v46|
	v_max3_f32 v216, v216, |v50|, |v54|
	v_max3_f32 v216, v216, |v58|, |v62|
	v_max3_f32 v216, v216, |v66|, |v70|
	v_max3_f32 v216, v216, |v74|, |v78|
	v_max3_f32 v216, v216, |v82|, |v86|
	v_max3_f32 v216, v216, |v90|, |v94|
	v_max3_f32 v216, v216, |v98|, |v102|
	v_max3_f32 v216, v216, |v106|, |v110|
	v_max3_f32 v216, v216, |v114|, |v118|
	v_max3_f32 v216, v216, |v122|, |v126|
	v_max_f32_e64 v216, v216, |v130|
	v_max3_f32 v217, |v7|, |v11|, |v15|
	v_max3_f32 v217, v217, |v19|, |v23|
	v_max3_f32 v217, v217, |v27|, |v31|
	v_max3_f32 v217, v217, |v35|, |v39|
	v_max3_f32 v217, v217, |v43|, |v47|
	v_max3_f32 v217, v217, |v51|, |v55|
	v_max3_f32 v217, v217, |v59|, |v63|
	v_max3_f32 v217, v217, |v67|, |v71|
	v_max3_f32 v217, v217, |v75|, |v79|
	v_max3_f32 v217, v217, |v83|, |v87|
	v_max3_f32 v217, v217, |v91|, |v95|
	v_max3_f32 v217, v217, |v99|, |v103|
	v_max3_f32 v217, v217, |v107|, |v111|
	v_max3_f32 v217, v217, |v115|, |v119|
	v_max3_f32 v217, v217, |v123|, |v127|
	v_max_f32_e64 v217, v217, |v131|
	v_max3_f32 v218, |v8|, |v12|, |v16|
	v_max3_f32 v218, v218, |v20|, |v24|
	v_max3_f32 v218, v218, |v28|, |v32|
	v_max3_f32 v218, v218, |v36|, |v40|
	v_max3_f32 v218, v218, |v44|, |v48|
	v_max3_f32 v218, v218, |v52|, |v56|
	v_max3_f32 v218, v218, |v60|, |v64|
	v_max3_f32 v218, v218, |v68|, |v72|
	v_max3_f32 v218, v218, |v76|, |v80|
	v_max3_f32 v218, v218, |v84|, |v88|
	v_max3_f32 v218, v218, |v92|, |v96|
	v_max3_f32 v218, v218, |v100|, |v104|
	v_max3_f32 v218, v218, |v108|, |v112|
	v_max3_f32 v218, v218, |v116|, |v120|
	v_max3_f32 v218, v218, |v124|, |v128|
	v_max_f32_e64 v218, v218, |v132|
	v_max3_f32 v219, |v9|, |v13|, |v17|
	v_max3_f32 v219, v219, |v21|, |v25|
	v_max3_f32 v219, v219, |v29|, |v33|
	v_max3_f32 v219, v219, |v37|, |v41|
	v_max3_f32 v219, v219, |v45|, |v49|
	v_max3_f32 v219, v219, |v53|, |v57|
	v_max3_f32 v219, v219, |v61|, |v65|
	v_max3_f32 v219, v219, |v69|, |v73|
	v_max3_f32 v219, v219, |v77|, |v81|
	v_max3_f32 v219, v219, |v85|, |v89|
	v_max3_f32 v219, v219, |v93|, |v97|
	v_max3_f32 v219, v219, |v101|, |v105|
	v_max3_f32 v219, v219, |v109|, |v113|
	v_max3_f32 v219, v219, |v117|, |v121|
	v_max3_f32 v219, v219, |v125|, |v129|
	v_max_f32_e64 v219, v219, |v133|
	ds_bpermute_b32 v174, v192, v216
	ds_bpermute_b32 v175, v192, v217
	ds_bpermute_b32 v176, v192, v218
	ds_bpermute_b32 v177, v192, v219
	s_waitcnt lgkmcnt(0)
	v_max_f32_e32 v216, v216, v174
	v_max_f32_e32 v217, v217, v175
	v_max_f32_e32 v218, v218, v176
	v_max_f32_e32 v219, v219, v177
	ds_bpermute_b32 v174, v193, v216
	ds_bpermute_b32 v175, v193, v217
	ds_bpermute_b32 v176, v193, v218
	ds_bpermute_b32 v177, v193, v219
	s_waitcnt lgkmcnt(0)
	v_max_f32_e32 v216, v216, v174
	v_max_f32_e32 v217, v217, v175
	v_max_f32_e32 v218, v218, v176
	v_max_f32_e32 v219, v219, v177
	ds_bpermute_b32 v174, v194, v216
	ds_bpermute_b32 v175, v194, v217
	ds_bpermute_b32 v176, v194, v218
	ds_bpermute_b32 v177, v194, v219
	s_waitcnt lgkmcnt(0)
	v_max_f32_e32 v216, v216, v174
	v_max_f32_e32 v217, v217, v175
	v_max_f32_e32 v218, v218, v176
	v_max_f32_e32 v219, v219, v177
	s_mov_b64 s[70:71], exec
	s_mov_b64 exec, 0xff
	ds_write_b128 v172, v[216:219]
	s_mov_b64 exec, s[70:71]
	s_waitcnt lgkmcnt(0)
	s_add_u32 s16, s16, 1
	s_mov_b64 s[70:71], exec
	s_mov_b64 exec, 1
	ds_add_u32 v250, v251
	s_mov_b64 exec, s[70:71]
	s_lshl_b32 s3, s16, 2
	s_movk_i32 s54, 0x4000
.Lc32_gates_hbar:
	ds_read_b32 v174, v250
	s_waitcnt lgkmcnt(0)
	v_readfirstlane_b32 s10, v174
	s_nop 3
	s_cmp_ge_u32 s10, s3
	s_cbranch_scc1 .Lc32_gates_hbar_ok
	s_sub_u32 s54, s54, 1
	s_cmp_lg_u32 s54, 0
	s_cbranch_scc1 .Lc32_gates_hbar
.Lc32_gates_hbar_ok:
	ds_read_b128 v[140:143], v173 offset:0
	ds_read_b128 v[144:147], v173 offset:128
	ds_read_b128 v[148:151], v173 offset:256
	ds_read_b128 v[152:155], v173 offset:384
	s_waitcnt lgkmcnt(0)
	v_max3_f32 v220, v140, v144, v148
	v_max_f32_e32 v220, v220, v152
	v_max3_f32 v221, v141, v145, v149
	v_max_f32_e32 v221, v221, v153
	v_max3_f32 v222, v142, v146, v150
	v_max_f32_e32 v222, v222, v154
	v_max3_f32 v223, v143, v147, v151
	v_max_f32_e32 v223, v223, v155
	s_lshl_b32 s3, s11, 10
	s_lshl_b32 s10, s12, 8
	s_add_u32 s10, s10, s3
	s_add_u32 s66, s50, s10
	s_addc_u32 s67, s51, 0
	s_mov_b64 s[70:71], exec
	s_cmp_lg_u32 s15, 0
	s_cbranch_scc1 .Lc32_gates_nopub
	s_mov_b64 exec, 0xff
	v_mov_b32_e32 v249, s53
	v_mov_b32_e32 v248, v220
	global_store_dwordx2 v195, v[248:249], s[66:67] offset:0 sc0 sc1
	s_nop 1
	v_mov_b32_e32 v248, v221
	global_store_dwordx2 v195, v[248:249], s[66:67] offset:8 sc0 sc1
	s_nop 1
	v_mov_b32_e32 v248, v222
	global_store_dwordx2 v195, v[248:249], s[66:67] offset:16 sc0 sc1
	s_nop 1
	v_mov_b32_e32 v248, v223
	global_store_dwordx2 v195, v[248:249], s[66:67] offset:24 sc0 sc1
	s_nop 1
.Lc32_gates_nopub:
	s_mov_b64 exec, 0xffffffff
	s_add_u32 s66, s50, s3
	s_addc_u32 s67, s51, 0
	s_movk_i32 s54, 0x800
.Lc32_gates_poll:
	global_load_dwordx2 v[240:241], v252, s[66:67] offset:0 sc0 sc1
	global_load_dwordx2 v[242:243], v252, s[66:67] offset:8 sc0 sc1
	global_load_dwordx2 v[244:245], v252, s[66:67] offset:16 sc0 sc1
	global_load_dwordx2 v[246:247], v252, s[66:67] offset:24 sc0 sc1
	s_waitcnt vmcnt(0)
	v_cmp_ne_u32_e32 vcc, s53, v241
	v_cmp_ne_u32_e64 s[56:57], s53, v243
	s_nop 1
	s_or_b64 vcc, vcc, s[56:57]
	v_cmp_ne_u32_e64 s[56:57], s53, v245
	s_nop 1
	s_or_b64 vcc, vcc, s[56:57]
	v_cmp_ne_u32_e64 s[56:57], s53, v247
	s_nop 1
	s_or_b64 vcc, vcc, s[56:57]
	s_nop 1
	s_and_b64 vcc, vcc, exec
	s_cbranch_vccz .Lc32_gates_got
	s_sleep 1
	s_sub_u32 s54, s54, 1
	s_cmp_lg_u32 s54, 0
	s_cbranch_scc1 .Lc32_gates_poll
.Lc32_gates_got:
	v_mov_b32_e32 v220, v240
	v_mov_b32_e32 v221, v242
	v_mov_b32_e32 v222, v244
	v_mov_b32_e32 v223, v246
	ds_bpermute_b32 v174, v192, v220
	ds_bpermute_b32 v175, v192, v221
	ds_bpermute_b32 v176, v192, v222
	ds_bpermute_b32 v177, v192, v223
	s_waitcnt lgkmcnt(0)
	v_max_f32_e32 v220, v220, v174
	v_max_f32_e32 v221, v221, v175
	v_max_f32_e32 v222, v222, v176
	v_max_f32_e32 v223, v223, v177
	ds_bpermute_b32 v174, v193, v220
	ds_bpermute_b32 v175, v193, v221
	ds_bpermute_b32 v176, v193, v222
	ds_bpermute_b32 v177, v193, v223
	s_waitcnt lgkmcnt(0)
	v_max_f32_e32 v220, v220, v174
	v_max_f32_e32 v221, v221, v175
	v_max_f32_e32 v222, v222, v176
	v_max_f32_e32 v223, v223, v177
	s_mov_b64 exec, s[70:71]
	v_lshlrev_b32_e32 v174, 2, v137
	ds_bpermute_b32 v175, v174, v220
	ds_bpermute_b32 v176, v174, v221
	ds_bpermute_b32 v177, v174, v222
	ds_bpermute_b32 v178, v174, v223
	s_waitcnt lgkmcnt(0)
	v_mov_b32_e32 v220, v175
	v_mov_b32_e32 v221, v176
	v_mov_b32_e32 v222, v177
	v_mov_b32_e32 v223, v178
	s_or_b32 s3, s15, s12
	s_cmp_lg_u32 s3, 0
	s_cbranch_scc1 .Lc32_gates_nocm
	s_lshl_b32 s3, s2, 2
	s_add_u32 s56, s34, s3
	s_addc_u32 s57, s35, 0
	s_add_u32 s56, s56, 0x80000
	s_addc_u32 s57, s57, 0
	s_mov_b64 s[70:71], exec
	s_mov_b64 exec, 0xff
	global_store_dwordx4 v230, v[220:223], s[56:57]
	s_mov_b64 exec, s[70:71]

.Lc32_ffn1_loop:
	s_lshl_b32 s2, s0, 5
	s_add_u32 s53, s53, 1
	s_cmp_ge_u32 s2, 0x2b00
	s_cselect_b32 s75, 128, 0
	s_cselect_b32 s3, 0x2b00, 0
	s_sub_u32 s3, s2, s3
	s_lshr_b32 s60, s3, 7
	s_lshl_b32 s60, s60, 8
	s_and_b32 s3, s3, 127
	s_add_u32 s60, s60, s3
	s_add_u32 s60, s60, s75
	s_lshl_b32 s63, s11, 10
	s_add_u32 s63, s63, s17
	s_lshl_b32 s3, s15, 7
	s_add_u32 s3, s3, s63
	v_add_u32_e32 v172, s3, v230
	v_add_u32_e32 v173, s63, v230
	s_waitcnt vmcnt(0)
	v_max3_f32 v216, |v6|, |v10|, |v14|
	v_max3_f32 v216, v216, |v18|, |v22|
	v_max3_f32 v216, v216, |v26|, |v30|
	v_max3_f32 v216, v216, |v34|, |v38|
	v_max3_f32 v216, v216, |v42|, |v46|
	v_max3_f32 v216, v216, |v50|, |v54|
	v_max3_f32 v216, v216, |v58|, |v62|
	v_max3_f32 v216, v216, |v66|, |v70|
	v_max3_f32 v216, v216, |v74|, |v78|
	v_max3_f32 v216, v216, |v82|, |v86|
	v_max3_f32 v216, v216, |v90|, |v94|
	v_max3_f32 v216, v216, |v98|, |v102|
	v_max3_f32 v216, v216, |v106|, |v110|
	v_max3_f32 v216, v216, |v114|, |v118|
	v_max3_f32 v216, v216, |v122|, |v126|
	v_max_f32_e64 v216, v216, |v130|
	v_max3_f32 v217, |v7|, |v11|, |v15|
	v_max3_f32 v217, v217, |v19|, |v23|
	v_max3_f32 v217, v217, |v27|, |v31|
	v_max3_f32 v217, v217, |v35|, |v39|
	v_max3_f32 v217, v217, |v43|, |v47|
	v_max3_f32 v217, v217, |v51|, |v55|
	v_max3_f32 v217, v217, |v59|, |v63|
	v_max3_f32 v217, v217, |v67|, |v71|
	v_max3_f32 v217, v217, |v75|, |v79|
	v_max3_f32 v217, v217, |v83|, |v87|
	v_max3_f32 v217, v217, |v91|, |v95|
	v_max3_f32 v217, v217, |v99|, |v103|
	v_max3_f32 v217, v217, |v107|, |v111|
	v_max3_f32 v217, v217, |v115|, |v119|
	v_max3_f32 v217, v217, |v123|, |v127|
	v_max_f32_e64 v217, v217, |v131|
	v_max3_f32 v218, |v8|, |v12|, |v16|
	v_max3_f32 v218, v218, |v20|, |v24|
	v_max3_f32 v218, v218, |v28|, |v32|
	v_max3_f32 v218, v218, |v36|, |v40|
	v_max3_f32 v218, v218, |v44|, |v48|
	v_max3_f32 v218, v218, |v52|, |v56|
	v_max3_f32 v218, v218, |v60|, |v64|
	v_max3_f32 v218, v218, |v68|, |v72|
	v_max3_f32 v218, v218, |v76|, |v80|
	v_max3_f32 v218, v218, |v84|, |v88|
	v_max3_f32 v218, v218, |v92|, |v96|
	v_max3_f32 v218, v218, |v100|, |v104|
	v_max3_f32 v218, v218, |v108|, |v112|
	v_max3_f32 v218, v218, |v116|, |v120|
	v_max3_f32 v218, v218, |v124|, |v128|
	v_max_f32_e64 v218, v218, |v132|
	v_max3_f32 v219, |v9|, |v13|, |v17|
	v_max3_f32 v219, v219, |v21|, |v25|
	v_max3_f32 v219, v219, |v29|, |v33|
	v_max3_f32 v219, v219, |v37|, |v41|
	v_max3_f32 v219, v219, |v45|, |v49|
	v_max3_f32 v219, v219, |v53|, |v57|
	v_max3_f32 v219, v219, |v61|, |v65|
	v_max3_f32 v219, v219, |v69|, |v73|
	v_max3_f32 v219, v219, |v77|, |v81|
	v_max3_f32 v219, v219, |v85|, |v89|
	v_max3_f32 v219, v219, |v93|, |v97|
	v_max3_f32 v219, v219, |v101|, |v105|
	v_max3_f32 v219, v219, |v109|, |v113|
	v_max3_f32 v219, v219, |v117|, |v121|
	v_max3_f32 v219, v219, |v125|, |v129|
	v_max_f32_e64 v219, v219, |v133|
	ds_bpermute_b32 v174, v192, v216
	ds_bpermute_b32 v175, v192, v217
	ds_bpermute_b32 v176, v192, v218
	ds_bpermute_b32 v177, v192, v219
	s_waitcnt lgkmcnt(0)
	v_max_f32_e32 v216, v216, v174
	v_max_f32_e32 v217, v217, v175
	v_max_f32_e32 v218, v218, v176
	v_max_f32_e32 v219, v219, v177
	ds_bpermute_b32 v174, v193, v216
	ds_bpermute_b32 v175, v193, v217
	ds_bpermute_b32 v176, v193, v218
	ds_bpermute_b32 v177, v193, v219
	s_waitcnt lgkmcnt(0)
	v_max_f32_e32 v216, v216, v174
	v_max_f32_e32 v217, v217, v175
	v_max_f32_e32 v218, v218, v176
	v_max_f32_e32 v219, v219, v177
	ds_bpermute_b32 v174, v194, v216
	ds_bpermute_b32 v175, v194, v217
	ds_bpermute_b32 v176, v194, v218
	ds_bpermute_b32 v177, v194, v219
	s_waitcnt lgkmcnt(0)
	v_max_f32_e32 v216, v216, v174
	v_max_f32_e32 v217, v217, v175
	v_max_f32_e32 v218, v218, v176
	v_max_f32_e32 v219, v219, v177
	s_mov_b64 s[70:71], exec
	s_mov_b64 exec, 0xff
	ds_write_b128 v172, v[216:219]
	s_mov_b64 exec, s[70:71]
	s_waitcnt lgkmcnt(0)
	s_add_u32 s16, s16, 1
	s_mov_b64 s[70:71], exec
	s_mov_b64 exec, 1
	ds_add_u32 v250, v251
	s_mov_b64 exec, s[70:71]
	s_lshl_b32 s3, s16, 2
	s_movk_i32 s54, 0x4000

.Lc32_ffn1_got:
	v_mov_b32_e32 v220, v240
	v_mov_b32_e32 v221, v242
	v_mov_b32_e32 v222, v244
	v_mov_b32_e32 v223, v246
	ds_bpermute_b32 v174, v192, v220
	ds_bpermute_b32 v175, v192, v221
	ds_bpermute_b32 v176, v192, v222
	ds_bpermute_b32 v177, v192, v223
	s_waitcnt lgkmcnt(0)
	v_max_f32_e32 v220, v220, v174
	v_max_f32_e32 v221, v221, v175
	v_max_f32_e32 v222, v222, v176
	v_max_f32_e32 v223, v223, v177
	ds_bpermute_b32 v174, v193, v220
	ds_bpermute_b32 v175, v193, v221
	ds_bpermute_b32 v176, v193, v222
	ds_bpermute_b32 v177, v193, v223
	s_waitcnt lgkmcnt(0)
	v_max_f32_e32 v220, v220, v174
	v_max_f32_e32 v221, v221, v175
	v_max_f32_e32 v222, v222, v176
	v_max_f32_e32 v223, v223, v177
	s_mov_b64 exec, s[70:71]
	v_lshlrev_b32_e32 v174, 2, v137
	ds_bpermute_b32 v175, v174, v220
	ds_bpermute_b32 v176, v174, v221
	ds_bpermute_b32 v177, v174, v222
	ds_bpermute_b32 v178, v174, v223
	s_waitcnt lgkmcnt(0)
	v_mov_b32_e32 v220, v175
	v_mov_b32_e32 v221, v176
	v_mov_b32_e32 v222, v177
	v_mov_b32_e32 v223, v178
	s_or_b32 s3, s15, s12
	s_cmp_lg_u32 s3, 0
	s_cbranch_scc1 .Lc32_ffn1_nocm
	s_lshl_b32 s3, s2, 2
	s_add_u32 s56, s34, s3
	s_addc_u32 s57, s35, 0
	s_add_u32 s56, s56, 0x40000
	s_addc_u32 s57, s57, 0
	s_mov_b64 s[70:71], exec
	s_mov_b64 exec, 0xff
	global_store_dwordx4 v230, v[220:223], s[56:57]
	s_mov_b64 exec, s[70:71]

.Lc32_mixer_got:
	v_mov_b32_e32 v220, v240
	v_mov_b32_e32 v221, v242
	v_mov_b32_e32 v222, v244
	v_mov_b32_e32 v223, v246
	ds_bpermute_b32 v174, v192, v220
	ds_bpermute_b32 v175, v192, v221
	ds_bpermute_b32 v176, v192, v222
	ds_bpermute_b32 v177, v192, v223
	s_waitcnt lgkmcnt(0)
	v_max_f32_e32 v220, v220, v174
	v_max_f32_e32 v221, v221, v175
	v_max_f32_e32 v222, v222, v176
	v_max_f32_e32 v223, v223, v177
	ds_bpermute_b32 v174, v193, v220
	ds_bpermute_b32 v175, v193, v221
	ds_bpermute_b32 v176, v193, v222
	ds_bpermute_b32 v177, v193, v223
	s_waitcnt lgkmcnt(0)
	v_max_f32_e32 v220, v220, v174
	v_max_f32_e32 v221, v221, v175
	v_max_f32_e32 v222, v222, v176
	v_max_f32_e32 v223, v223, v177
	s_mov_b64 exec, s[70:71]
	v_lshlrev_b32_e32 v174, 2, v137
	ds_bpermute_b32 v175, v174, v220
	ds_bpermute_b32 v176, v174, v221
	ds_bpermute_b32 v177, v174, v222
	ds_bpermute_b32 v178, v174, v223
	s_waitcnt lgkmcnt(0)
	v_mov_b32_e32 v220, v175
	v_mov_b32_e32 v221, v176
	v_mov_b32_e32 v222, v177
	v_mov_b32_e32 v223, v178
	s_or_b32 s3, s15, s12
	s_cmp_lg_u32 s3, 0
	s_cbranch_scc1 .Lc32_mixer_nocm
	s_lshl_b32 s3, s2, 2
	s_add_u32 s56, s34, s3
	s_addc_u32 s57, s35, 0
	s_add_u32 s56, s56, 0xe0000
	s_addc_u32 s57, s57, 0
	s_mov_b64 s[70:71], exec
	s_mov_b64 exec, 0xff
	global_store_dwordx4 v230, v[220:223], s[56:57]
	s_mov_b64 exec, s[70:71]

.LBB0_484:
	v_mbcnt_lo_u32_b32 v135, -1, 0
	v_mbcnt_hi_u32_b32 v135, -1, v135
	v_lshrrev_b32_e32 v136, 3, v135
	v_and_b32_e32 v137, 7, v135
	v_lshlrev_b32_e32 v230, 4, v137
	v_lshlrev_b32_e32 v195, 5, v137
	v_lshlrev_b32_e32 v231, 15, v137
	v_lshl_add_u32 v231, v136, 3, v231
	v_readlane_b32 s7, v254, 17
	v_readlane_b32 s1, v254, 16
	v_readlane_b32 s13, v254, 15
	s_mov_b32 s11, 0x42fe0000
	s_mov_b32 s5, 0
	s_and_b32 s60, s13, 3
	s_lshr_b32 s13, s13, 2
	s_and_b32 s15, s1, 3
	s_lshr_b32 s3, s1, 2
	s_lshl_b32 s13, s13, 1
	s_add_u32 s13, s13, s3
	s_lshl_b32 s20, s3, 11
	s_add_u32 s20, s20, 0x21000
	s_lshl_b32 s3, s3, 4
	s_add_u32 s3, s3, 0x22000
	v_mov_b32_e32 v250, s3
	v_mov_b32_e32 v251, 0
	ds_write_b32 v250, v251
	v_mov_b32_e32 v251, 1
	v_and_b32_e32 v252, 31, v135
	v_lshlrev_b32_e32 v252, 5, v252
	s_mov_b32 s17, 0
	s_mov_b32 s61, 64
	s_lshl_b32 s64, s60, 10
	s_lshl_b32 s3, s15, 8
	s_add_u32 s64, s64, s3
	s_lshl_b32 s3, s13, 11
	s_add_u32 s3, s3, 0x8000
	s_cmp_ge_u32 s13, 112
	s_cselect_b32 s4, 0x48000, 0
	s_add_u32 s3, s3, s4
	s_add_u32 s62, s34, s3
	s_addc_u32 s63, s35, 0
	s_waitcnt lgkmcnt(0)
	s_barrier
	v_lshlrev_b32_e32 v139, 10, v137
	v_lshl_add_u32 v139, v136, 2, v139
	v_add_u32_e32 v139, s7, v139
	v_lshlrev_b32_e32 v174, 2, v135
	v_xor_b32_e32 v192, 0x20, v174
	v_xor_b32_e32 v193, 0x40, v174
	v_xor_b32_e32 v194, 0x80, v174
	v_lshrrev_b32_e32 v175, 4, v135
	v_and_b32_e32 v176, 15, v135
	v_lshlrev_b32_e32 v212, 8, v175
	v_lshl_add_u32 v212, v176, 4, v212
	v_add_u32_e32 v212, s7, v212
	v_lshlrev_b32_e32 v213, 12, v175
	v_lshl_add_u32 v213, v176, 4, v213
	v_readlane_b32 s52, v255, 61
	v_readlane_b32 s53, v255, 62
	v_mul_u32_u24_e32 v138, 0x56000, v136
	v_lshl_add_u32 v138, v137, 4, v138
	s_mul_i32 s3, s64, 0x15800
	s_nop 1
	s_add_u32 s52, s52, s3
	s_addc_u32 s53, s53, 0
	s_mov_b32 s0, s13
	s_cmp_ge_u32 s0, 0x2b0
	s_cbranch_scc1 .Lc32p3_ffn2_done
	s_lshl_b32 s3, s0, 7
	s_add_u32 s54, s52, s3
	s_addc_u32 s55, s53, 0
	global_load_dwordx4 v[6:9], v138, s[54:55]
	s_add_u32 s54, s54, 0x15800
	s_addc_u32 s55, s55, 0
	global_load_dwordx4 v[10:13], v138, s[54:55]
	s_add_u32 s54, s54, 0x15800
	s_addc_u32 s55, s55, 0
	global_load_dwordx4 v[14:17], v138, s[54:55]
	s_add_u32 s54, s54, 0x15800
	s_addc_u32 s55, s55, 0
	global_load_dwordx4 v[18:21], v138, s[54:55]
	s_add_u32 s54, s54, 0x26f800
	s_addc_u32 s55, s55, 0
	global_load_dwordx4 v[22:25], v138, s[54:55]
	s_add_u32 s54, s54, 0x15800
	s_addc_u32 s55, s55, 0
	global_load_dwordx4 v[26:29], v138, s[54:55]
	s_add_u32 s54, s54, 0x15800
	s_addc_u32 s55, s55, 0
	global_load_dwordx4 v[30:33], v138, s[54:55]
	s_add_u32 s54, s54, 0x15800
	s_addc_u32 s55, s55, 0
	global_load_dwordx4 v[34:37], v138, s[54:55]
	s_add_u32 s54, s54, 0x26f800
	s_addc_u32 s55, s55, 0
	global_load_dwordx4 v[38:41], v138, s[54:55]
	s_add_u32 s54, s54, 0x15800
	s_addc_u32 s55, s55, 0
	global_load_dwordx4 v[42:45], v138, s[54:55]
	s_add_u32 s54, s54, 0x15800
	s_addc_u32 s55, s55, 0
	global_load_dwordx4 v[46:49], v138, s[54:55]
	s_add_u32 s54, s54, 0x15800
	s_addc_u32 s55, s55, 0
	global_load_dwordx4 v[50:53], v138, s[54:55]
	s_add_u32 s54, s54, 0x26f800
	s_addc_u32 s55, s55, 0
	global_load_dwordx4 v[54:57], v138, s[54:55]
	s_add_u32 s54, s54, 0x15800
	s_addc_u32 s55, s55, 0
	global_load_dwordx4 v[58:61], v138, s[54:55]
	s_add_u32 s54, s54, 0x15800
	s_addc_u32 s55, s55, 0
	global_load_dwordx4 v[62:65], v138, s[54:55]
	s_add_u32 s54, s54, 0x15800
	s_addc_u32 s55, s55, 0
	global_load_dwordx4 v[66:69], v138, s[54:55]
	s_add_u32 s54, s54, 0x26f800
	s_addc_u32 s55, s55, 0
	global_load_dwordx4 v[70:73], v138, s[54:55]
	s_add_u32 s54, s54, 0x15800
	s_addc_u32 s55, s55, 0
	global_load_dwordx4 v[74:77], v138, s[54:55]
	s_add_u32 s54, s54, 0x15800
	s_addc_u32 s55, s55, 0
	global_load_dwordx4 v[78:81], v138, s[54:55]
	s_add_u32 s54, s54, 0x15800
	s_addc_u32 s55, s55, 0
	global_load_dwordx4 v[82:85], v138, s[54:55]
	s_add_u32 s54, s54, 0x26f800
	s_addc_u32 s55, s55, 0
	global_load_dwordx4 v[86:89], v138, s[54:55]
	s_add_u32 s54, s54, 0x15800
	s_addc_u32 s55, s55, 0
	global_load_dwordx4 v[90:93], v138, s[54:55]
	s_add_u32 s54, s54, 0x15800
	s_addc_u32 s55, s55, 0
	global_load_dwordx4 v[94:97], v138, s[54:55]
	s_add_u32 s54, s54, 0x15800
	s_addc_u32 s55, s55, 0
	global_load_dwordx4 v[98:101], v138, s[54:55]
	s_add_u32 s54, s54, 0x26f800
	s_addc_u32 s55, s55, 0
	global_load_dwordx4 v[102:105], v138, s[54:55]
	s_add_u32 s54, s54, 0x15800
	s_addc_u32 s55, s55, 0
	global_load_dwordx4 v[106:109], v138, s[54:55]
	s_add_u32 s54, s54, 0x15800
	s_addc_u32 s55, s55, 0
	global_load_dwordx4 v[110:113], v138, s[54:55]
	s_add_u32 s54, s54, 0x15800
	s_addc_u32 s55, s55, 0
	global_load_dwordx4 v[114:117], v138, s[54:55]
	s_add_u32 s54, s54, 0x26f800
	s_addc_u32 s55, s55, 0
	global_load_dwordx4 v[118:121], v138, s[54:55]
	s_add_u32 s54, s54, 0x15800
	s_addc_u32 s55, s55, 0
	global_load_dwordx4 v[122:125], v138, s[54:55]
	s_add_u32 s54, s54, 0x15800
	s_addc_u32 s55, s55, 0
	global_load_dwordx4 v[126:129], v138, s[54:55]
	s_add_u32 s54, s54, 0x15800
	s_addc_u32 s55, s55, 0
	global_load_dwordx4 v[130:133], v138, s[54:55]
.Lc32p3_ffn2_loop:
	s_lshl_b32 s2, s0, 5
	s_add_u32 s61, s61, 1
	s_cmp_ge_u32 s2, 0x2b00
	s_cselect_b32 s12, 128, 0
	s_cselect_b32 s3, 0x2b00, 0
	s_sub_u32 s3, s2, s3
	s_lshr_b32 s6, s3, 7
	s_lshl_b32 s6, s6, 8
	s_and_b32 s3, s3, 127
	s_add_u32 s6, s6, s3
	s_add_u32 s6, s6, s12
	s_lshl_b32 s10, s5, 10
	s_add_u32 s10, s10, s20
	s_lshl_b32 s3, s15, 7
	s_add_u32 s3, s3, s10
	v_add_u32_e32 v172, s3, v230
	v_add_u32_e32 v173, s10, v230
	s_waitcnt vmcnt(0)
	v_max3_f32 v216, |v6|, |v10|, |v14|
	v_max3_f32 v216, v216, |v18|, |v22|
	v_max3_f32 v216, v216, |v26|, |v30|
	v_max3_f32 v216, v216, |v34|, |v38|
	v_max3_f32 v216, v216, |v42|, |v46|
	v_max3_f32 v216, v216, |v50|, |v54|
	v_max3_f32 v216, v216, |v58|, |v62|
	v_max3_f32 v216, v216, |v66|, |v70|
	v_max3_f32 v216, v216, |v74|, |v78|
	v_max3_f32 v216, v216, |v82|, |v86|
	v_max3_f32 v216, v216, |v90|, |v94|
	v_max3_f32 v216, v216, |v98|, |v102|
	v_max3_f32 v216, v216, |v106|, |v110|
	v_max3_f32 v216, v216, |v114|, |v118|
	v_max3_f32 v216, v216, |v122|, |v126|
	v_max_f32_e64 v216, v216, |v130|
	v_max3_f32 v217, |v7|, |v11|, |v15|
	v_max3_f32 v217, v217, |v19|, |v23|
	v_max3_f32 v217, v217, |v27|, |v31|
	v_max3_f32 v217, v217, |v35|, |v39|
	v_max3_f32 v217, v217, |v43|, |v47|
	v_max3_f32 v217, v217, |v51|, |v55|
	v_max3_f32 v217, v217, |v59|, |v63|
	v_max3_f32 v217, v217, |v67|, |v71|
	v_max3_f32 v217, v217, |v75|, |v79|
	v_max3_f32 v217, v217, |v83|, |v87|
	v_max3_f32 v217, v217, |v91|, |v95|
	v_max3_f32 v217, v217, |v99|, |v103|
	v_max3_f32 v217, v217, |v107|, |v111|
	v_max3_f32 v217, v217, |v115|, |v119|
	v_max3_f32 v217, v217, |v123|, |v127|
	v_max_f32_e64 v217, v217, |v131|
	v_max3_f32 v218, |v8|, |v12|, |v16|
	v_max3_f32 v218, v218, |v20|, |v24|
	v_max3_f32 v218, v218, |v28|, |v32|
	v_max3_f32 v218, v218, |v36|, |v40|
	v_max3_f32 v218, v218, |v44|, |v48|
	v_max3_f32 v218, v218, |v52|, |v56|
	v_max3_f32 v218, v218, |v60|, |v64|
	v_max3_f32 v218, v218, |v68|, |v72|
	v_max3_f32 v218, v218, |v76|, |v80|
	v_max3_f32 v218, v218, |v84|, |v88|
	v_max3_f32 v218, v218, |v92|, |v96|
	v_max3_f32 v218, v218, |v100|, |v104|
	v_max3_f32 v218, v218, |v108|, |v112|
	v_max3_f32 v218, v218, |v116|, |v120|
	v_max3_f32 v218, v218, |v124|, |v128|
	v_max_f32_e64 v218, v218, |v132|
	v_max3_f32 v219, |v9|, |v13|, |v17|
	v_max3_f32 v219, v219, |v21|, |v25|
	v_max3_f32 v219, v219, |v29|, |v33|
	v_max3_f32 v219, v219, |v37|, |v41|
	v_max3_f32 v219, v219, |v45|, |v49|
	v_max3_f32 v219, v219, |v53|, |v57|
	v_max3_f32 v219, v219, |v61|, |v65|
	v_max3_f32 v219, v219, |v69|, |v73|
	v_max3_f32 v219, v219, |v77|, |v81|
	v_max3_f32 v219, v219, |v85|, |v89|
	v_max3_f32 v219, v219, |v93|, |v97|
	v_max3_f32 v219, v219, |v101|, |v105|
	v_max3_f32 v219, v219, |v109|, |v113|
	v_max3_f32 v219, v219, |v117|, |v121|
	v_max3_f32 v219, v219, |v125|, |v129|
	v_max_f32_e64 v219, v219, |v133|
	ds_bpermute_b32 v174, v192, v216
	ds_bpermute_b32 v175, v192, v217
	ds_bpermute_b32 v176, v192, v218
	ds_bpermute_b32 v177, v192, v219
	s_waitcnt lgkmcnt(0)
	v_max_f32_e32 v216, v216, v174
	v_max_f32_e32 v217, v217, v175
	v_max_f32_e32 v218, v218, v176
	v_max_f32_e32 v219, v219, v177
	ds_bpermute_b32 v174, v193, v216
	ds_bpermute_b32 v175, v193, v217
	ds_bpermute_b32 v176, v193, v218
	ds_bpermute_b32 v177, v193, v219
	s_waitcnt lgkmcnt(0)
	v_max_f32_e32 v216, v216, v174
	v_max_f32_e32 v217, v217, v175
	v_max_f32_e32 v218, v218, v176
	v_max_f32_e32 v219, v219, v177
	ds_bpermute_b32 v174, v194, v216
	ds_bpermute_b32 v175, v194, v217
	ds_bpermute_b32 v176, v194, v218
	ds_bpermute_b32 v177, v194, v219
	s_waitcnt lgkmcnt(0)
	v_max_f32_e32 v216, v216, v174
	v_max_f32_e32 v217, v217, v175
	v_max_f32_e32 v218, v218, v176
	v_max_f32_e32 v219, v219, v177
	s_mov_b64 s[58:59], exec
	s_mov_b64 exec, 0xff
	ds_write_b128 v172, v[216:219]
	s_mov_b64 exec, s[58:59]
	s_waitcnt lgkmcnt(0)
	s_add_u32 s17, s17, 1
	s_mov_b64 s[58:59], exec
	s_mov_b64 exec, 1
	ds_add_u32 v250, v251
	s_mov_b64 exec, s[58:59]
	s_lshl_b32 s3, s17, 2
	s_movk_i32 s65, 0x4000
.Lc32p3_ffn2_hbar:
	ds_read_b32 v174, v250
	s_waitcnt lgkmcnt(0)
	v_readfirstlane_b32 s4, v174
	s_nop 3
	s_cmp_ge_u32 s4, s3
	s_cbranch_scc1 .Lc32p3_ffn2_hbar_ok
	s_sub_u32 s65, s65, 1
	s_cmp_lg_u32 s65, 0
	s_cbranch_scc1 .Lc32p3_ffn2_hbar
.Lc32p3_ffn2_hbar_ok:
	ds_read_b128 v[140:143], v173 offset:0
	ds_read_b128 v[144:147], v173 offset:128
	ds_read_b128 v[148:151], v173 offset:256
	ds_read_b128 v[152:155], v173 offset:384
	s_waitcnt lgkmcnt(0)
	v_max3_f32 v220, v140, v144, v148
	v_max_f32_e32 v220, v220, v152
	v_max3_f32 v221, v141, v145, v149
	v_max_f32_e32 v221, v221, v153
	v_max3_f32 v222, v142, v146, v150
	v_max_f32_e32 v222, v222, v154
	v_max3_f32 v223, v143, v147, v151
	v_max_f32_e32 v223, v223, v155
	s_lshl_b32 s3, s5, 10
	s_lshl_b32 s4, s60, 8
	s_add_u32 s4, s4, s3
	s_add_u32 s66, s62, s4
	s_addc_u32 s67, s63, 0
	s_mov_b64 s[58:59], exec
	s_cmp_lg_u32 s15, 0
	s_cbranch_scc1 .Lc32p3_ffn2_nopub
	s_mov_b64 exec, 0xff
	v_mov_b32_e32 v249, s61
	v_mov_b32_e32 v248, v220
	global_store_dwordx2 v195, v[248:249], s[66:67] offset:0 sc0 sc1
	s_nop 1
	v_mov_b32_e32 v248, v221
	global_store_dwordx2 v195, v[248:249], s[66:67] offset:8 sc0 sc1
	s_nop 1
	v_mov_b32_e32 v248, v222
	global_store_dwordx2 v195, v[248:249], s[66:67] offset:16 sc0 sc1
	s_nop 1
	v_mov_b32_e32 v248, v223
	global_store_dwordx2 v195, v[248:249], s[66:67] offset:24 sc0 sc1
	s_nop 1
.Lc32p3_ffn2_nopub:
	s_mov_b64 exec, 0xffffffff
	s_add_u32 s66, s62, s3
	s_addc_u32 s67, s63, 0
	s_movk_i32 s65, 0x800
.Lc32p3_ffn2_poll:
	global_load_dwordx2 v[240:241], v252, s[66:67] offset:0 sc0 sc1
	global_load_dwordx2 v[242:243], v252, s[66:67] offset:8 sc0 sc1
	global_load_dwordx2 v[244:245], v252, s[66:67] offset:16 sc0 sc1
	global_load_dwordx2 v[246:247], v252, s[66:67] offset:24 sc0 sc1
	s_waitcnt vmcnt(0)
	v_cmp_ne_u32_e32 vcc, s61, v241
	v_cmp_ne_u32_e64 s[54:55], s61, v243
	s_nop 1
	s_or_b64 vcc, vcc, s[54:55]
	v_cmp_ne_u32_e64 s[54:55], s61, v245
	s_nop 1
	s_or_b64 vcc, vcc, s[54:55]
	v_cmp_ne_u32_e64 s[54:55], s61, v247
	s_nop 1
	s_or_b64 vcc, vcc, s[54:55]
	s_nop 1
	s_and_b64 vcc, vcc, exec
	s_cbranch_vccz .Lc32p3_ffn2_got
	s_sleep 1
	s_sub_u32 s65, s65, 1
	s_cmp_lg_u32 s65, 0
	s_cbranch_scc1 .Lc32p3_ffn2_poll
.Lc32p3_ffn2_got:
	v_mov_b32_e32 v220, v240
	v_mov_b32_e32 v221, v242
	v_mov_b32_e32 v222, v244
	v_mov_b32_e32 v223, v246
	ds_bpermute_b32 v174, v192, v220
	ds_bpermute_b32 v175, v192, v221
	ds_bpermute_b32 v176, v192, v222
	ds_bpermute_b32 v177, v192, v223
	s_waitcnt lgkmcnt(0)
	v_max_f32_e32 v220, v220, v174
	v_max_f32_e32 v221, v221, v175
	v_max_f32_e32 v222, v222, v176
	v_max_f32_e32 v223, v223, v177
	ds_bpermute_b32 v174, v193, v220
	ds_bpermute_b32 v175, v193, v221
	ds_bpermute_b32 v176, v193, v222
	ds_bpermute_b32 v177, v193, v223
	s_waitcnt lgkmcnt(0)
	v_max_f32_e32 v220, v220, v174
	v_max_f32_e32 v221, v221, v175
	v_max_f32_e32 v222, v222, v176
	v_max_f32_e32 v223, v223, v177
	s_mov_b64 exec, s[58:59]
	v_lshlrev_b32_e32 v174, 2, v137
	ds_bpermute_b32 v175, v174, v220
	ds_bpermute_b32 v176, v174, v221
	ds_bpermute_b32 v177, v174, v222
	ds_bpermute_b32 v178, v174, v223
	s_waitcnt lgkmcnt(0)
	v_mov_b32_e32 v220, v175
	v_mov_b32_e32 v221, v176
	v_mov_b32_e32 v222, v177
	v_mov_b32_e32 v223, v178
	s_or_b32 s3, s15, s60
	s_cmp_lg_u32 s3, 0
	s_cbranch_scc1 .Lc32p3_ffn2_nocm
	s_lshl_b32 s3, s2, 2
	s_add_u32 s54, s34, s3
	s_addc_u32 s55, s35, 0
	s_add_u32 s54, s54, 0x60000
	s_addc_u32 s55, s55, 0
	s_mov_b64 s[58:59], exec
	s_mov_b64 exec, 0xff
	global_store_dwordx4 v230, v[220:223], s[54:55]
	s_mov_b64 exec, s[58:59]
